# weight-tile conversion moved to idle GEMM tail rounds with pipelined converter; layer-0 W_out epilogue reads x directly (no residual copy for prompt rows); copy_x unrolled
# speedup vs baseline: 1.0826x; 1.0120x over previous
; #define LAS __attribute__((address_space(3)))
; __device__ __forceinline__ int tidx() { int t = threadIdx.x; asm volatile("" : "+v"(t)); return t; }
;     typedef RecCfg<MIX> C;
;     const int tid = tidx(), s = tid >> 3, c4 = (tid & 7) * 4;
;     const Slot sl = slot_of<SAMPLE>(chunk, s, sg);
;     f32x4 o = *(const LAS f32x4*)(L + C::OFF_O + s * 32 + c4);
;     if constexpr (MIX == 3) o = o + *(const LAS f32x4*)(L + C::OFF_XSD + s * 32 + c4);
;     u32x2 w; w.x = pkh(o[0], o[1]); w.y = pkh(o[2], o[3]);
;     if (c4 < nv) *(u32x2*)(raw + (size_t)sl.row * DM + mixer * 256 + head * 64 + vcol0 + c4) = w;
; }
; __device__ __forceinline__ void phase_rec(const Params& p, int l, LAS unsigned char* lds) {
;     ...
;         else { rec_unit_chunked<3>(p, l, lds, sg, head, vhalf); rec_unit<1, false, true>(p, l, lds, sg, head, vhalf * 32); rec_unit<0, false, true>(p, l, lds, sg, head, vhalf * 32);
;             if (l == 0) convert_tiles(N_TILES_WIN0 + 4800 + bi * 14, N_TILES_WIN0 + 4800 + bi * 14 + 14, 1, (LAS float*)lds); }
.LBB0_220:
	s_or_b64 exec, exec, s[10:11]
	v_mov_b32_e32 v0, v202
	s_waitcnt lgkmcnt(0)
	s_barrier
	s_add_i32 s2, 0, 0x10400
	v_ashrrev_i32_e32 v1, 3, v0
	v_lshlrev_b32_e32 v0, 2, v0
	v_and_b32_e32 v6, 28, v0
	v_and_b32_e32 v0, -4, v1
	v_add_u32_e32 v0, s26, v0
	v_and_or_b32 v4, v1, 3, v0
	v_lshlrev_b32_e32 v0, 7, v1
	v_lshlrev_b32_e32 v1, 2, v6
	v_add3_u32 v0, s2, v0, v1
	ds_read_b128 v[0:3], v0
	v_ashrrev_i32_e32 v5, 31, v4
	s_mov_b32 s89, s79
	v_lshlrev_b32_e32 v16, 1, v6
	v_readlane_b32 s2, v252, 46
	s_waitcnt lgkmcnt(0)
	v_cvt_pk_f16_f32 v0, v0, v1
	v_cvt_pk_f16_f32 v1, v2, v3
	v_lshlrev_b64 v[2:3], 11, v[4:5]
	v_lshl_add_u64 v[2:3], s[8:9], 0, v[2:3]
	v_lshl_add_u64 v[2:3], v[2:3], 0, s[78:79]
	v_lshl_add_u64 v[2:3], v[2:3], 0, s[88:89]
	v_lshl_add_u64 v[2:3], v[2:3], 0, v[16:17]
	v_add_co_u32_e32 v2, vcc, 0x3500000, v2
	v_readlane_b32 s3, v252, 47
	s_nop 0
	v_addc_co_u32_e32 v3, vcc, 0, v3, vcc
	global_store_dwordx2 v[2:3], v[0:1], off
	s_barrier
	s_load_dwordx2 s[82:83], s[0:1], 0xe8
	v_readlane_b32 s60, v252, 28
	s_andn2_b64 vcc, exec, s[2:3]
	v_readlane_b32 s61, v252, 29
	s_waitcnt lgkmcnt(0)
	v_readlane_b32 s83, v252, 33
	s_mov_b32 s23, 0x41a00000
	s_mov_b32 s62, 0x3f2aaaab
	s_mov_b32 s63, 0x3f317218
	s_mov_b32 s64, 0x33800000
	s_mov_b32 s58, 0x81ff
	s_mov_b32 s66, 0x358637bd
	s_mov_b64 s[68:69], 0x1010
	s_mov_b64 s[70:71], 0x1210
	s_mov_b64 s[72:73], 0x400000
	s_mov_b64 s[54:55], 0x200
	s_mov_b64 s[56:57], 0x2000
	s_mul_i32 s59, s35, 0x84
	s_branch .LBB0_256
	s_cmpk_gt_i32 s77, 0xff4d
	s_cselect_b64 s[10:11], -1, 0
	s_and_b64 s[2:3], s[10:11], exec
	s_mov_b64 s[2:3], s[0:1]
	s_mul_i32 s36, s77, 14
	s_cselect_b32 s4, 0xfffff2c0, 0
	s_load_dwordx2 s[2:3], s[2:3], 0xe0
	s_add_i32 s42, s36, s4
	s_addk_i32 s42, 0x1700
	s_and_b64 s[4:5], s[10:11], exec
	s_cselect_b32 s4, 0x1a80000, 0
	s_waitcnt lgkmcnt(0)
	s_add_u32 s8, s2, s4
	s_addc_u32 s9, s3, 0
	s_cmpk_gt_i32 s42, 0x43f
	s_mov_b64 s[12:13], -1
	s_cbranch_scc0 .LBB0_230
	s_cmpk_gt_u32 s42, 0x53f
	s_cbranch_scc0 .LBB0_227
	s_and_b64 s[2:3], s[10:11], exec
	s_cselect_b32 s3, 0x400000, 0
	s_cmpk_gt_u32 s42, 0x93f
	s_cbranch_scc0 .LBB0_225
	s_mov_b64 s[4:5], s[0:1]
	s_load_dwordx2 s[4:5], s[4:5], 0xc8
	s_add_i32 s2, s42, 0xfffff6c0
	s_lshl_b32 s6, s3, 2
	s_mov_b64 s[12:13], 0
	s_waitcnt lgkmcnt(0)
	s_add_u32 s6, s4, s6
	s_addc_u32 s7, s5, 0
	s_add_u32 s4, s8, 0x1280000
	s_addc_u32 s5, s9, 0
	s_and_b32 s26, s36, 62
	s_lshr_b32 s2, s2, 6

; #define LAS __attribute__((address_space(3)))
; __device__ __forceinline__ int tidx() { int t = threadIdx.x; asm volatile("" : "+v"(t)); return t; }
; __device__ __forceinline__ const float* pin(int i) { return kargs()->in[i]; }
; __device__ __forceinline__ float* pout() { return kargs()->out; }
; __device__ __forceinline__ void copy_x_rows(int r0, int n) {
;     const f32x4* xp = (const f32x4*)pin(0); const f32x4* xs = (const f32x4*)pin(1); f32x4* X = (f32x4*)(pout() + O_Y);
;     for (int i = tidx(); i < n * 256; i += 512) { const size_t e = (size_t)r0 * 256 + i;
;         X[e] = e < (size_t)TP * 256 ? xp[e] : xs[e - (size_t)TP * 256]; }
; }
; __device__ __forceinline__ void phase_rec(const Params& p, int l, LAS unsigned char* lds) {
;     ...
;         else if (mixer == 2) { rec_unit_chunked<2>(p, l, lds, sg, head, vhalf); rec_unit<2, false, true>(p, l, lds, sg, head, vhalf * 32); rec_unit<3, false, true>(p, l, lds, sg, head, vhalf * 32);
;             if (l == 0) { convert_tiles(N_TILES_WIN0 + 2560 + bi * 35, N_TILES_WIN0 + 2560 + bi * 35 + 35, 1, (LAS float*)lds); copy_x_rows((64 + bi) * 132, 132); } }
.LBB0_288:
	s_or_b64 exec, exec, s[8:9]
	v_mov_b32_e32 v0, v202
	s_waitcnt lgkmcnt(0)
	s_barrier
	s_add_i32 s2, 0, 0x14c00
	v_ashrrev_i32_e32 v1, 3, v0
	v_lshlrev_b32_e32 v0, 2, v0
	v_and_b32_e32 v10, 28, v0
	v_and_b32_e32 v0, -4, v1
	v_add_u32_e32 v0, s26, v0
	v_lshlrev_b32_e32 v4, 7, v1
	v_lshlrev_b32_e32 v5, 2, v10
	v_and_or_b32 v8, v1, 3, v0
	v_add3_u32 v0, s2, v4, v5
	v_add3_u32 v4, s29, v4, v5
	ds_read_b128 v[0:3], v0
	ds_read_b128 v[4:7], v4
	v_ashrrev_i32_e32 v9, 31, v8
	s_mov_b32 s89, s79
	v_lshlrev_b32_e32 v16, 1, v10
	v_readlane_b32 s2, v252, 46
	s_waitcnt lgkmcnt(0)
	v_pk_add_f32 v[2:3], v[2:3], v[6:7]
	v_pk_add_f32 v[0:1], v[0:1], v[4:5]
	v_readlane_b32 s3, v252, 47
	v_cvt_pk_f16_f32 v0, v0, v1
	v_cvt_pk_f16_f32 v1, v2, v3
	v_lshlrev_b64 v[2:3], 11, v[8:9]
	v_lshl_add_u64 v[2:3], s[4:5], 0, v[2:3]
	v_lshl_add_u64 v[2:3], v[2:3], 0, s[78:79]
	v_lshl_add_u64 v[2:3], v[2:3], 0, s[88:89]
	v_lshl_add_u64 v[2:3], v[2:3], 0, v[16:17]
	v_add_co_u32_e32 v2, vcc, 0x3500000, v2
	v_readlane_b32 s60, v252, 28
	s_nop 0
	v_addc_co_u32_e32 v3, vcc, 0, v3, vcc
	s_andn2_b64 vcc, exec, s[2:3]
	v_readlane_b32 s61, v252, 29
	s_mov_b32 s23, 0x41a00000
	s_mov_b32 s62, 0x3f2aaaab
	s_mov_b32 s63, 0x3f317218
	s_mov_b32 s64, 0x33800000
	s_mov_b32 s58, 0x81ff
	s_mov_b32 s66, 0x358637bd
	s_mov_b64 s[68:69], 0x1010
	s_mov_b64 s[70:71], 0x1210
	s_mov_b64 s[72:73], 0x400000
	s_mov_b64 s[54:55], 0x200
	s_mov_b64 s[56:57], 0x2000
	s_mov_b32 s59, s77
	s_mov_b32 s77, s35
	v_readlane_b32 s35, v252, 63
	global_store_dwordx2 v[2:3], v[0:1], off offset:1536
	s_barrier
	s_cbranch_vccnz .LBB0_333
	s_cmp_lt_u32 s77, 60
	s_cbranch_scc1 .LBB0_333
	s_branch .LBB0_329
	s_cmp_gt_i32 s77, -8
	s_cselect_b64 s[10:11], -1, 0
	s_and_b64 s[2:3], s[10:11], exec
	s_mov_b64 s[2:3], s[0:1]
	s_mul_i32 s36, s77, 35
	s_cselect_b32 s4, 0xfffff2c0, 0
	s_load_dwordx2 s[2:3], s[2:3], 0xe0
	s_add_i32 s42, s36, s4
	s_addk_i32 s42, 0xe40
	s_and_b64 s[4:5], s[10:11], exec
	s_cselect_b32 s4, 0x1a80000, 0
	s_waitcnt lgkmcnt(0)
	s_add_u32 s8, s2, s4
	s_addc_u32 s9, s3, 0
	s_cmpk_gt_i32 s42, 0x43f
	s_mov_b64 s[12:13], -1
	s_cbranch_scc0 .LBB0_298
	s_cmpk_gt_u32 s42, 0x53f
	s_cbranch_scc0 .LBB0_295
	s_and_b64 s[2:3], s[10:11], exec
	s_cselect_b32 s3, 0x400000, 0
	s_cmpk_gt_u32 s42, 0x93f
	s_cbranch_scc0 .LBB0_293
	s_mov_b64 s[4:5], s[0:1]
	s_load_dwordx2 s[4:5], s[4:5], 0xc8
	s_add_i32 s2, s42, 0xfffff6c0
	s_lshl_b32 s6, s3, 2
	s_mov_b64 s[12:13], 0
	s_waitcnt lgkmcnt(0)
	s_add_u32 s6, s4, s6
	s_addc_u32 s7, s5, 0
	s_add_u32 s4, s8, 0x1280000
	s_addc_u32 s5, s9, 0
	s_and_b32 s26, s36, 63
	s_lshr_b32 s2, s2, 6

; __device__ __forceinline__ int tidx() { int t = threadIdx.x; asm volatile("" : "+v"(t)); return t; }
; __device__ __forceinline__ const float* pin(int i) { return kargs()->in[i]; }
; __device__ __forceinline__ float* pout() { return kargs()->out; }
; __device__ __forceinline__ void copy_x_rows(int r0, int n) {
;     const f32x4* xp = (const f32x4*)pin(0); const f32x4* xs = (const f32x4*)pin(1); f32x4* X = (f32x4*)(pout() + O_Y);
;     for (int i = tidx(); i < n * 256; i += 512) { const size_t e = (size_t)r0 * 256 + i;
;         X[e] = e < (size_t)TP * 256 ? xp[e] : xs[e - (size_t)TP * 256]; }
; }
.LBB0_331:
	v_lshl_add_u64 v[8:9], s[6:7], 0, v[0:1]
	v_cmp_gt_u64_e32 vcc, s[72:73], v[8:9]
	v_lshl_add_u64 v[0:1], v[0:1], 0, s[54:55]
	s_nop 0
	v_cndmask_b32_e32 v9, v5, v7, vcc
	v_cndmask_b32_e32 v8, v4, v6, vcc
	global_load_dwordx4 v[140:143], v[8:9], off
	v_lshl_add_u64 v[4:5], v[4:5], 0, s[56:57]
	v_lshl_add_u64 v[6:7], v[6:7], 0, s[56:57]
	v_lshl_add_u64 v[8:9], s[6:7], 0, v[0:1]
	v_cmp_gt_u64_e32 vcc, s[72:73], v[8:9]
	v_lshl_add_u64 v[0:1], v[0:1], 0, s[54:55]
	s_nop 0
	v_cndmask_b32_e32 v9, v5, v7, vcc
	v_cndmask_b32_e32 v8, v4, v6, vcc
	global_load_dwordx4 v[144:147], v[8:9], off
	v_lshl_add_u64 v[4:5], v[4:5], 0, s[56:57]
	v_lshl_add_u64 v[6:7], v[6:7], 0, s[56:57]
	v_lshl_add_u64 v[8:9], s[6:7], 0, v[0:1]
	v_cmp_gt_u64_e32 vcc, s[72:73], v[8:9]
	v_lshl_add_u64 v[0:1], v[0:1], 0, s[54:55]
	s_nop 0
	v_cndmask_b32_e32 v9, v5, v7, vcc
	v_cndmask_b32_e32 v8, v4, v6, vcc
	global_load_dwordx4 v[148:151], v[8:9], off
	v_lshl_add_u64 v[4:5], v[4:5], 0, s[56:57]
	v_lshl_add_u64 v[6:7], v[6:7], 0, s[56:57]
	v_lshl_add_u64 v[8:9], s[6:7], 0, v[0:1]
	v_cmp_gt_u64_e32 vcc, s[72:73], v[8:9]
	v_lshl_add_u64 v[0:1], v[0:1], 0, s[54:55]
	s_nop 0
	v_cndmask_b32_e32 v9, v5, v7, vcc
	v_cndmask_b32_e32 v8, v4, v6, vcc
	global_load_dwordx4 v[152:155], v[8:9], off
	v_lshl_add_u64 v[4:5], v[4:5], 0, s[56:57]
	v_lshl_add_u64 v[6:7], v[6:7], 0, s[56:57]
	v_lshl_add_u64 v[8:9], s[6:7], 0, v[0:1]
	v_cmp_gt_u64_e32 vcc, s[72:73], v[8:9]
	v_lshl_add_u64 v[0:1], v[0:1], 0, s[54:55]
	s_nop 0
	v_cndmask_b32_e32 v9, v5, v7, vcc
	v_cndmask_b32_e32 v8, v4, v6, vcc
	global_load_dwordx4 v[156:159], v[8:9], off
	v_lshl_add_u64 v[4:5], v[4:5], 0, s[56:57]
	v_lshl_add_u64 v[6:7], v[6:7], 0, s[56:57]
	v_lshl_add_u64 v[8:9], s[6:7], 0, v[0:1]
	v_cmp_gt_u64_e32 vcc, s[72:73], v[8:9]
	v_lshl_add_u64 v[0:1], v[0:1], 0, s[54:55]
	s_nop 0
	v_cndmask_b32_e32 v9, v5, v7, vcc
	v_cndmask_b32_e32 v8, v4, v6, vcc
	global_load_dwordx4 v[160:163], v[8:9], off
	v_lshl_add_u64 v[4:5], v[4:5], 0, s[56:57]
	v_lshl_add_u64 v[6:7], v[6:7], 0, s[56:57]
	v_add_u32_e32 v12, 0xfffffe00, v0
	v_cmp_lt_i32_e32 vcc, s58, v12
	s_or_b64 s[8:9], vcc, s[8:9]
	s_waitcnt vmcnt(0)
	global_store_dwordx4 v[2:3], v[140:143], off
	v_lshl_add_u64 v[2:3], v[2:3], 0, s[56:57]
	global_store_dwordx4 v[2:3], v[144:147], off
	v_lshl_add_u64 v[2:3], v[2:3], 0, s[56:57]
	global_store_dwordx4 v[2:3], v[148:151], off
	v_lshl_add_u64 v[2:3], v[2:3], 0, s[56:57]
	global_store_dwordx4 v[2:3], v[152:155], off
	v_lshl_add_u64 v[2:3], v[2:3], 0, s[56:57]
	global_store_dwordx4 v[2:3], v[156:159], off
	v_lshl_add_u64 v[2:3], v[2:3], 0, s[56:57]
	global_store_dwordx4 v[2:3], v[160:163], off
	v_lshl_add_u64 v[2:3], v[2:3], 0, s[56:57]
	s_andn2_b64 exec, exec, s[8:9]
	s_cbranch_execnz .LBB0_331

; #define LAS __attribute__((address_space(3)))
; __device__ __forceinline__ void phase_rec(const Params& p, int l, LAS unsigned char* lds) {
;     ...
;         if (mixer == 0) { rec_unit<0, true, false>(p, l, lds, sg, head, vhalf * 32);
;             if (l == 0) { convert_tiles(N_TILES_WIN0 + bi * 40, N_TILES_WIN0 + bi * 40 + 40, 1, (LAS float*)lds); copy_x_rows(bi * 132, 132); } }
.LBB0_355:
	s_or_b64 exec, exec, s[4:5]
	v_readlane_b32 s2, v252, 46
	v_readlane_b32 s3, v252, 47
	s_andn2_b64 vcc, exec, s[2:3]
	s_cbranch_vccnz .LBB0_402
	s_branch .LBB0_402
	s_cmp_gt_i32 s77, 57
	s_cselect_b64 s[10:11], -1, 0
	s_and_b64 s[2:3], s[10:11], exec
	s_mov_b64 s[2:3], s[0:1]
	s_mul_i32 s25, s77, 40
	s_cselect_b32 s4, 0xfffff2c0, 0
	s_load_dwordx2 s[2:3], s[2:3], 0xe0
	s_add_i32 s42, s25, s4
	s_add_i32 s26, s42, 0x440
	s_and_b64 s[4:5], s[10:11], exec
	s_cselect_b32 s4, 0x1a80000, 0
	s_waitcnt lgkmcnt(0)
	s_add_u32 s8, s2, s4
	s_addc_u32 s9, s3, 0
	s_cmpk_gt_i32 s26, 0x43f
	s_mov_b64 s[12:13], -1
	s_cbranch_scc0 .LBB0_365
	s_cmpk_gt_u32 s26, 0x53f
	s_cbranch_scc0 .LBB0_362
	s_and_b64 s[2:3], s[10:11], exec
	s_cselect_b32 s3, 0x400000, 0
	s_cmpk_gt_u32 s26, 0x93f
	s_cbranch_scc0 .LBB0_360
	s_mov_b64 s[4:5], s[0:1]
	s_load_dwordx2 s[4:5], s[4:5], 0xc8
	s_add_i32 s2, s26, 0xfffff6c0
	s_lshl_b32 s6, s3, 2
	s_mov_b64 s[12:13], 0
	s_waitcnt lgkmcnt(0)
	s_add_u32 s6, s4, s6
	s_addc_u32 s7, s5, 0
	s_add_u32 s4, s8, 0x1280000
	s_addc_u32 s5, s9, 0
	s_and_b32 s22, s25, 56
	s_lshr_b32 s2, s2, 6

;     __device__ __forceinline__ void operator()(const f32x4 (&acc)[2][2][4][2], const Unit& u, int wr, int wc, int fr, int fq) const {
;     ...
;                 for (int m = 0; m < 4; ++m) { float* rowp = C + (size_t)(row0 + ai * HALF + m * 16) * ldc + col0;
; #pragma unroll
;                     for (int bj = 0; bj < 2; ++bj)
; #pragma unroll
;                         for (int n = 0; n < 2; ++n) { float* q = rowp + bj * HALF + n * 16; const f32x4 v = acc[ai][bj][m][n];
;                             if (u.k0 < 0) *(f32x4*)(scr + (size_t)u.sl * TS * DM + (q - C) - (size_t)64 * BM * ldc) = v;
;                             else *(f32x4*)q = *(f32x4*)q + v; } }
.LBB0_864:
	s_and_b64 vcc, exec, s[6:7]
	s_cbranch_vccz .LBB0_814
	v_or_b32_e32 v16, s3, v160
	v_lshl_add_u64 v[146:147], v[16:17], 2, s[52:53]
	v_lshl_add_u64 v[148:149], v[144:145], 2, v[146:147]
	s_mov_b64 s[6:7], -1
	s_and_b64 vcc, exec, s[4:5]
	s_cbranch_vccz .LBB0_867
	s_mov_b64 s[6:7], 0x10000
	s_mov_b64 s[40:41], 0x80000
	v_lshl_add_u64 v[150:151], v[148:149], 0, s[6:7]
	v_lshl_add_u64 v[162:163], v[148:149], 0, s[40:41]
	v_lshl_add_u64 v[152:153], v[150:151], 0, s[6:7]
	v_lshl_add_u64 v[164:165], v[162:163], 0, s[6:7]
	v_lshl_add_u64 v[154:155], v[152:153], 0, s[6:7]
	v_lshl_add_u64 v[198:199], v[164:165], 0, s[6:7]
	v_lshl_add_u64 v[200:201], v[198:199], 0, s[6:7]
	s_mov_b64 s[100:101], 0
	s_cmp_lg_u32 s27, 5
	s_cbranch_scc1 .Lepi_nodelta
	s_load_dwordx2 s[4:5], s[0:1], 0x0
	s_load_dwordx2 s[98:99], s[0:1], 0xd8
	s_waitcnt lgkmcnt(0)
	s_sub_u32 s100, s4, s98
	s_subb_u32 s101, s5, s99
.Lepi_nodelta:
	v_lshl_add_u64 v[230:231], v[148:149], 0, s[100:101]
	global_load_dwordx4 v[166:169], v[230:231], off
	global_load_dwordx4 v[170:173], v[230:231], off offset:64
	global_load_dwordx4 v[174:177], v[230:231], off offset:512
	global_load_dwordx4 v[178:181], v[230:231], off offset:576
	v_lshl_add_u64 v[230:231], v[150:151], 0, s[100:101]
	global_load_dwordx4 v[182:185], v[230:231], off
	global_load_dwordx4 v[186:189], v[230:231], off offset:64
	global_load_dwordx4 v[190:193], v[230:231], off offset:512
	global_load_dwordx4 v[194:197], v[230:231], off offset:576
	s_waitcnt vmcnt(4)
	v_pk_add_f32 v[126:127], v[126:127], v[166:167]
	v_pk_add_f32 v[128:129], v[128:129], v[168:169]
	v_pk_add_f32 v[122:123], v[122:123], v[170:171]
	v_pk_add_f32 v[124:125], v[124:125], v[172:173]
	v_pk_add_f32 v[118:119], v[118:119], v[174:175]
	v_pk_add_f32 v[120:121], v[120:121], v[176:177]
	v_pk_add_f32 v[114:115], v[114:115], v[178:179]
	v_pk_add_f32 v[116:117], v[116:117], v[180:181]
	global_store_dwordx4 v[148:149], v[126:129], off
	global_store_dwordx4 v[148:149], v[122:125], off offset:64
	global_store_dwordx4 v[148:149], v[118:121], off offset:512
	global_store_dwordx4 v[148:149], v[114:117], off offset:576
	v_lshl_add_u64 v[230:231], v[152:153], 0, s[100:101]
	global_load_dwordx4 v[166:169], v[230:231], off
	global_load_dwordx4 v[170:173], v[230:231], off offset:64
	global_load_dwordx4 v[174:177], v[230:231], off offset:512
	global_load_dwordx4 v[178:181], v[230:231], off offset:576
	s_waitcnt vmcnt(8)
	v_pk_add_f32 v[110:111], v[110:111], v[182:183]
	v_pk_add_f32 v[112:113], v[112:113], v[184:185]
	v_pk_add_f32 v[106:107], v[106:107], v[186:187]
	v_pk_add_f32 v[108:109], v[108:109], v[188:189]
	v_pk_add_f32 v[102:103], v[102:103], v[190:191]
	v_pk_add_f32 v[104:105], v[104:105], v[192:193]
	v_pk_add_f32 v[98:99], v[98:99], v[194:195]
	v_pk_add_f32 v[100:101], v[100:101], v[196:197]
	global_store_dwordx4 v[150:151], v[110:113], off
	global_store_dwordx4 v[150:151], v[106:109], off offset:64
	global_store_dwordx4 v[150:151], v[102:105], off offset:512
	global_store_dwordx4 v[150:151], v[98:101], off offset:576
	v_lshl_add_u64 v[230:231], v[154:155], 0, s[100:101]
	global_load_dwordx4 v[182:185], v[230:231], off
	global_load_dwordx4 v[186:189], v[230:231], off offset:64
	global_load_dwordx4 v[190:193], v[230:231], off offset:512
	global_load_dwordx4 v[194:197], v[230:231], off offset:576
	s_waitcnt vmcnt(8)
	v_pk_add_f32 v[94:95], v[94:95], v[166:167]
	v_pk_add_f32 v[96:97], v[96:97], v[168:169]
	v_pk_add_f32 v[90:91], v[90:91], v[170:171]
	v_pk_add_f32 v[92:93], v[92:93], v[172:173]
	v_pk_add_f32 v[86:87], v[86:87], v[174:175]
	v_pk_add_f32 v[88:89], v[88:89], v[176:177]
	v_pk_add_f32 v[82:83], v[82:83], v[178:179]
	v_pk_add_f32 v[84:85], v[84:85], v[180:181]
	global_store_dwordx4 v[152:153], v[94:97], off
	global_store_dwordx4 v[152:153], v[90:93], off offset:64
	global_store_dwordx4 v[152:153], v[86:89], off offset:512
	global_store_dwordx4 v[152:153], v[82:85], off offset:576
	v_lshl_add_u64 v[230:231], v[162:163], 0, s[100:101]
	global_load_dwordx4 v[166:169], v[230:231], off
	global_load_dwordx4 v[170:173], v[230:231], off offset:64
	global_load_dwordx4 v[174:177], v[230:231], off offset:512
	global_load_dwordx4 v[178:181], v[230:231], off offset:576
	s_waitcnt vmcnt(8)
;     __device__ __forceinline__ void operator()(const f32x4 (&acc)[2][2][4][2], const Unit& u, int wr, int wc, int fr, int fq) const {
;     ...
;                 for (int m = 0; m < 4; ++m) { float* rowp = C + (size_t)(row0 + ai * HALF + m * 16) * ldc + col0;
; #pragma unroll
;                     for (int bj = 0; bj < 2; ++bj)
; #pragma unroll
;                         for (int n = 0; n < 2; ++n) { float* q = rowp + bj * HALF + n * 16; const f32x4 v = acc[ai][bj][m][n];
;                             if (u.k0 < 0) *(f32x4*)(scr + (size_t)u.sl * TS * DM + (q - C) - (size_t)64 * BM * ldc) = v;
;                             else *(f32x4*)q = *(f32x4*)q + v; } }
	v_pk_add_f32 v[78:79], v[78:79], v[182:183]
	v_pk_add_f32 v[80:81], v[80:81], v[184:185]
	v_pk_add_f32 v[74:75], v[74:75], v[186:187]
	v_pk_add_f32 v[76:77], v[76:77], v[188:189]
	v_pk_add_f32 v[70:71], v[70:71], v[190:191]
	v_pk_add_f32 v[72:73], v[72:73], v[192:193]
	v_pk_add_f32 v[66:67], v[66:67], v[194:195]
	v_pk_add_f32 v[68:69], v[68:69], v[196:197]
	global_store_dwordx4 v[154:155], v[78:81], off
	global_store_dwordx4 v[154:155], v[74:77], off offset:64
	global_store_dwordx4 v[154:155], v[70:73], off offset:512
	global_store_dwordx4 v[154:155], v[66:69], off offset:576
	v_lshl_add_u64 v[230:231], v[164:165], 0, s[100:101]
	global_load_dwordx4 v[182:185], v[230:231], off
	global_load_dwordx4 v[186:189], v[230:231], off offset:64
	global_load_dwordx4 v[190:193], v[230:231], off offset:512
	global_load_dwordx4 v[194:197], v[230:231], off offset:576
	s_waitcnt vmcnt(8)
	v_pk_add_f32 v[62:63], v[62:63], v[166:167]
	v_pk_add_f32 v[64:65], v[64:65], v[168:169]
	v_pk_add_f32 v[58:59], v[58:59], v[170:171]
	v_pk_add_f32 v[60:61], v[60:61], v[172:173]
	v_pk_add_f32 v[54:55], v[54:55], v[174:175]
	v_pk_add_f32 v[56:57], v[56:57], v[176:177]
	v_pk_add_f32 v[50:51], v[50:51], v[178:179]
	v_pk_add_f32 v[52:53], v[52:53], v[180:181]
	global_store_dwordx4 v[162:163], v[62:65], off
	global_store_dwordx4 v[162:163], v[58:61], off offset:64
	global_store_dwordx4 v[162:163], v[54:57], off offset:512
	global_store_dwordx4 v[162:163], v[50:53], off offset:576
	v_lshl_add_u64 v[230:231], v[198:199], 0, s[100:101]
	global_load_dwordx4 v[166:169], v[230:231], off
	global_load_dwordx4 v[170:173], v[230:231], off offset:64
	global_load_dwordx4 v[174:177], v[230:231], off offset:512
	global_load_dwordx4 v[178:181], v[230:231], off offset:576
	s_waitcnt vmcnt(8)
	v_pk_add_f32 v[46:47], v[46:47], v[182:183]
	v_pk_add_f32 v[48:49], v[48:49], v[184:185]
	v_pk_add_f32 v[42:43], v[42:43], v[186:187]
	v_pk_add_f32 v[44:45], v[44:45], v[188:189]
	v_pk_add_f32 v[38:39], v[38:39], v[190:191]
	v_pk_add_f32 v[40:41], v[40:41], v[192:193]
	v_pk_add_f32 v[34:35], v[34:35], v[194:195]
	v_pk_add_f32 v[36:37], v[36:37], v[196:197]
	global_store_dwordx4 v[164:165], v[46:49], off
	global_store_dwordx4 v[164:165], v[42:45], off offset:64
	global_store_dwordx4 v[164:165], v[38:41], off offset:512
	global_store_dwordx4 v[164:165], v[34:37], off offset:576
	v_lshl_add_u64 v[230:231], v[200:201], 0, s[100:101]
	global_load_dwordx4 v[182:185], v[230:231], off
	global_load_dwordx4 v[186:189], v[230:231], off offset:64
	global_load_dwordx4 v[190:193], v[230:231], off offset:512
	global_load_dwordx4 v[194:197], v[230:231], off offset:576
	s_waitcnt vmcnt(8)
	v_pk_add_f32 v[30:31], v[30:31], v[166:167]
	v_pk_add_f32 v[32:33], v[32:33], v[168:169]
	v_pk_add_f32 v[26:27], v[26:27], v[170:171]
	v_pk_add_f32 v[28:29], v[28:29], v[172:173]
	v_pk_add_f32 v[22:23], v[22:23], v[174:175]
	v_pk_add_f32 v[24:25], v[24:25], v[176:177]
	v_pk_add_f32 v[18:19], v[18:19], v[178:179]
	v_pk_add_f32 v[20:21], v[20:21], v[180:181]
	global_store_dwordx4 v[198:199], v[30:33], off
	global_store_dwordx4 v[198:199], v[26:29], off offset:64
	global_store_dwordx4 v[198:199], v[22:25], off offset:512
	global_store_dwordx4 v[198:199], v[18:21], off offset:576
	s_waitcnt vmcnt(4)
	v_pk_add_f32 v[12:13], v[12:13], v[182:183]
	v_pk_add_f32 v[14:15], v[14:15], v[184:185]
	v_pk_add_f32 v[8:9], v[8:9], v[186:187]
	v_pk_add_f32 v[10:11], v[10:11], v[188:189]
	v_pk_add_f32 v[4:5], v[4:5], v[190:191]
	v_pk_add_f32 v[6:7], v[6:7], v[192:193]
	v_pk_add_f32 v[0:1], v[0:1], v[194:195]
	v_pk_add_f32 v[2:3], v[2:3], v[196:197]
	global_store_dwordx4 v[200:201], v[12:15], off
	global_store_dwordx4 v[200:201], v[8:11], off offset:64
	global_store_dwordx4 v[200:201], v[4:7], off offset:512
	global_store_dwordx4 v[200:201], v[0:3], off offset:576
	s_branch .LBB0_814
	global_load_dwordx4 v[150:153], v[148:149], off
	s_mov_b64 s[6:7], 0
	s_waitcnt vmcnt(0)
	v_pk_add_f32 v[152:153], v[128:129], v[152:153]
	v_pk_add_f32 v[150:151], v[126:127], v[150:151]
	global_store_dwordx4 v[148:149], v[150:153], off

; __device__ __forceinline__ TileJob tile_job(int t) {
;     constexpr int n_in = 16 * (PN / 64), n_out = 16 * 16, n_up = 16 * 64, n_dn = 64 * 16, tot = n_in + n_out + n_up + n_dn;
;     const int l = t >= tot ? 1 : 0, u0 = t - l * tot;
;     f16_t* wt = (f16_t*)(pws() + WS_WT + l * WT_LAYER);
;     TileJob j;
;     if (u0 < n_in) { j = TileJob{pin(9) + (size_t)l * DM * PTOT, wt + WT_WIN / 2, DM, PTOT, u0 % 16, u0 / 16}; }
;     else if (u0 < n_in + n_out) { const int u = u0 - n_in; j = TileJob{pin(22) + (size_t)l * DM * DM, wt + WT_WOUT / 2, DM, DM, u % 16, u / 16}; }
;     else if (u0 < n_in + n_out + n_up) { const int u = u0 - n_in - n_out; j = TileJob{pin(24) + (size_t)l * DM * DFF, wt + WT_WUP / 2, DM, DFF, u % 16, u / 16}; }
;     else { const int u = u0 - n_in - n_out - n_up; j = TileJob{pin(25) + (size_t)l * DFF * DM, wt + WT_WDOWN / 2, DFF, DM, u % 64, u / 64}; }
;     return j;
; }
; __device__ __forceinline__ void tile_load(const TileJob& j, f32x4 (&v)[2]) {
;     const int tid = tidx(), k0 = j.tk * 64, n0 = j.tn * 64;
; #pragma unroll
;     for (int i = 0; i < 2; ++i) { const int r = (tid >> 4) + 32 * i, c = (tid & 15) * 4, n = n0 + c;
;         v[i] = (f32x4){0.f, 0.f, 0.f, 0.f};
;         if (n < j.Nreal) v[i] = *(const f32x4*)(j.W + (size_t)(k0 + r) * j.Nreal + n); }
; }
; __device__ __forceinline__ void tile_store(const TileJob& j, const f32x4 (&v)[2], LAS float* tile) {
;     const int tid = tidx(), k0 = j.tk * 64, n0 = j.tn * 64;
; #pragma unroll
;     for (int i = 0; i < 2; ++i) { const int r = (tid >> 4) + 32 * i, c = (tid & 15) * 4;
;         tile[r * 65 + c] = v[i][0]; tile[r * 65 + c + 1] = v[i][1]; tile[r * 65 + c + 2] = v[i][2]; tile[r * 65 + c + 3] = v[i][3]; }
;     __syncthreads();
;     { const int nl = tid >> 3, k8 = (tid & 7) * 8; u32x4 w;
;       w.x = pkh(tile[(k8 + 0) * 65 + nl], tile[(k8 + 1) * 65 + nl]); w.y = pkh(tile[(k8 + 2) * 65 + nl], tile[(k8 + 3) * 65 + nl]);
;       w.z = pkh(tile[(k8 + 4) * 65 + nl], tile[(k8 + 5) * 65 + nl]); w.w = pkh(tile[(k8 + 6) * 65 + nl], tile[(k8 + 7) * 65 + nl]);
;       *(u32x4*)(j.Bt + (size_t)(n0 + nl) * j.Kdim + k0 + k8) = w; }
;     __syncthreads();
; }
; __device__ __forceinline__ void convert_tiles(int t0, int t1, int step, LAS float* tile) {
;     int t = t0;
;     if (t < t1) {
;         TileJob cur = tile_job(t); f32x4 v[2]; tile_load(cur, v);
;         for (;;) {
.LBB0_996:
	v_readlane_b32 s52, v252, 34
	v_readlane_b32 s54, v252, 36
	v_readlane_b32 s56, v252, 38
	v_readlane_b32 s58, v252, 40
	v_readlane_b32 s70, v252, 42
	v_readlane_b32 s74, v252, 44
	v_readlane_b32 s34, v252, 31
	s_mov_b64 s[4:5], 0
	v_readlane_b32 s53, v252, 35
	v_readlane_b32 s55, v252, 37
	v_readlane_b32 s57, v252, 39
	v_readlane_b32 s59, v252, 41
	v_readlane_b32 s71, v252, 43
	v_readlane_b32 s75, v252, 45
	v_readlane_b32 s35, v252, 32
	s_cmp_eq_u32 s27, 1
	s_cbranch_scc1 .Lcvt_w1
	s_cmp_eq_u32 s27, 7
	s_cbranch_scc1 .Lcvt_w7
	s_cmp_eq_u32 s27, 10
	s_cbranch_scc1 .Lcvt_w10
	s_cmp_eq_u32 s27, 16
	s_cbranch_scc0 .Lcvt_none
	s_sub_u32 s40, s17, 32
	s_cbranch_scc1 .Lcvt_none
	s_mul_i32 s40, s40, 5
	s_add_u32 s40, s40, 0x1680
	s_add_u32 s41, s40, 5
	s_min_u32 s41, s41, 0x1a80
	s_branch .Lcvt_go
.Lcvt_w1:
	s_sub_u32 s40, s17, 0x62
	s_cbranch_scc1 .Lcvt_none
	s_mul_i32 s40, s40, 9
	s_add_u32 s40, s40, 0x440
	s_add_u32 s41, s40, 9
	s_min_u32 s41, s41, 0x940
	s_branch .Lcvt_go
.Lcvt_w7:
	s_sub_u32 s40, s17, 32
	s_cbranch_scc1 .Lcvt_none
	s_mul_i32 s40, s40, 10
	s_add_u32 s40, s40, 0x940
	s_add_u32 s41, s40, 10
	s_min_u32 s41, s41, 0x1180
	s_branch .Lcvt_go
.Lcvt_w10:
	s_sub_u32 s40, s17, 0x62
	s_cbranch_scc1 .Lcvt_none
	s_mul_i32 s40, s40, 9
	s_add_u32 s40, s40, 0x1180
	s_add_u32 s41, s40, 9
	s_min_u32 s41, s41, 0x1680
.Lcvt_go:
	s_cmp_ge_u32 s40, s41
	s_cbranch_scc1 .Lcvt_none
	s_load_dwordx2 s[2:3], s[0:1], 0x48
	s_load_dwordx2 s[6:7], s[0:1], 0xb0
	s_load_dwordx2 s[8:9], s[0:1], 0xc0
	s_load_dwordx2 s[10:11], s[0:1], 0xc8
	s_load_dwordx2 s[12:13], s[0:1], 0xe0
	v_lshrrev_b32_e32 v1, 4, v202
	v_and_b32_e32 v3, 15, v202
	v_lshlrev_b32_e32 v3, 2, v3
	v_lshlrev_b32_e32 v2, 2, v3
	v_lshrrev_b32_e32 v4, 3, v202
	v_and_b32_e32 v8, 7, v202
	v_lshlrev_b32_e32 v5, 4, v8
	v_lshlrev_b32_e32 v8, 3, v8
	s_movk_i32 s22, 0x104
	v_mad_u32_u24 v6, v1, s22, v2
	v_lshlrev_b32_e32 v9, 2, v4
	v_mad_u32_u24 v7, v8, s22, v9
	v_add_u32_e32 v10, 0x2080, v6
	v_add_u32_e32 v11, 0x410, v7
	s_waitcnt lgkmcnt(0)
	v_writelane_b32 v12, s2, 0
	v_writelane_b32 v12, s3, 1
	v_writelane_b32 v12, s6, 2
	v_writelane_b32 v12, s7, 3
	v_writelane_b32 v12, s8, 4
	v_writelane_b32 v12, s9, 5
	v_writelane_b32 v12, s10, 6
	v_writelane_b32 v12, s11, 7
	s_mov_b32 s26, s40
	s_sub_u32 s9, s41, 1
	s_min_u32 s26, s26, s9
	s_cmp_ge_u32 s26, 0xd40
	s_cselect_b32 s36, 1, 0
	s_cselect_b32 s30, 0xd40, 0
	s_sub_u32 s30, s26, s30
	s_movk_i32 s31, 6
	s_mov_b32 s2, 0x1000000
	s_movk_i32 s3, 0x400
	s_movk_i32 s6, 0x940
	s_mov_b32 s7, 0x1280000
	s_cmp_lt_u32 s30, 0x940
	s_cselect_b32 s31, 4, s31
	s_cselect_b32 s3, 0x1000, s3
	s_cselect_b32 s6, 0x540, s6
	s_cselect_b32 s7, 0xa80000, s7
	s_cselect_b32 s8, 0, 1
	s_cmp_lt_u32 s30, 0x540
	s_cselect_b32 s31, 2, s31
	s_cselect_b32 s2, 0x400000, s2
	s_cselect_b32 s3, 0x400, s3
	s_cselect_b32 s6, 0x440, s6
	s_cselect_b32 s7, 0x880000, s7
	s_cmp_lt_u32 s30, 0x440
	s_cselect_b32 s31, 0, s31
	s_cselect_b32 s2, 0x100c000, s2
	s_cselect_b32 s3, 0x100c, s3
	s_cselect_b32 s6, 0, s6
	s_cselect_b32 s7, 0, s7
	s_sub_u32 s30, s30, s6
	s_cmp_eq_u32 s8, 1
	s_cselect_b32 s9, 6, 4
	s_cselect_b32 s10, 63, 15
	s_movk_i32 s22, 0x800
	s_cselect_b32 s22, 0x2000, s22
	s_lshr_b32 s11, s30, s9
	s_and_b32 s10, s30, s10
	v_readlane_b32 s4, v12, s31
	s_add_u32 s31, s31, 1
	v_readlane_b32 s5, v12, s31
	s_mul_i32 s2, s2, s36
	s_lshl_b32 s9, s3, 2
	s_mul_i32 s8, s10, s9
	s_lshl_b32 s8, s8, 6
	s_add_u32 s2, s2, s8
	s_add_u32 s4, s4, s2
	s_addc_u32 s5, s5, 0
	s_mul_i32 s2, s11, s22
	s_lshl_b32 s2, s2, 6
	s_lshl_b32 s8, s10, 7
	s_add_u32 s2, s2, s8
	s_add_u32 s2, s2, s7
	s_mul_i32 s8, s36, 0x1a80000
	s_add_u32 s2, s2, s8
	s_add_u32 s42, s12, s2
	s_addc_u32 s43, s13, 0
	s_lshl_b32 s8, s11, 6
	s_sub_i32 s2, s3, s8
	v_cmp_gt_i32_e64 s[48:49], s2, v3
	s_lshl_b32 s8, s8, 2
	v_add_u32_e32 v13, s8, v2
	s_lshl_b32 s8, s9, 5
	s_add_u32 s6, s4, s8
	s_addc_u32 s7, s5, 0
	v_cndmask_b32_e64 v13, 0, v13, s[48:49]
	v_mad_u32_u24 v13, v1, s9, v13
	global_load_dwordx4 v[20:23], v13, s[4:5]
	global_load_dwordx4 v[24:27], v13, s[6:7]
	s_add_u32 s26, s40, 1
	s_sub_u32 s9, s41, 1
	s_min_u32 s26, s26, s9
	s_cmp_ge_u32 s26, 0xd40
	s_cselect_b32 s36, 1, 0
	s_cselect_b32 s30, 0xd40, 0
	s_sub_u32 s30, s26, s30
	s_movk_i32 s31, 6
	s_mov_b32 s2, 0x1000000
	s_movk_i32 s3, 0x400
	s_movk_i32 s6, 0x940
	s_mov_b32 s7, 0x1280000
	s_cmp_lt_u32 s30, 0x940
	s_cselect_b32 s31, 4, s31
	s_cselect_b32 s3, 0x1000, s3
	s_cselect_b32 s6, 0x540, s6
	s_cselect_b32 s7, 0xa80000, s7
	s_cselect_b32 s8, 0, 1
	s_cmp_lt_u32 s30, 0x540
	s_cselect_b32 s31, 2, s31
	s_cselect_b32 s2, 0x400000, s2
	s_cselect_b32 s3, 0x400, s3
	s_cselect_b32 s6, 0x440, s6
	s_cselect_b32 s7, 0x880000, s7
	s_cmp_lt_u32 s30, 0x440
	s_cselect_b32 s31, 0, s31
	s_cselect_b32 s2, 0x100c000, s2
	s_cselect_b32 s3, 0x100c, s3
	s_cselect_b32 s6, 0, s6
	s_cselect_b32 s7, 0, s7
	s_sub_u32 s30, s30, s6
	s_cmp_eq_u32 s8, 1
	s_cselect_b32 s9, 6, 4
	s_cselect_b32 s10, 63, 15
	s_movk_i32 s23, 0x800
	s_cselect_b32 s23, 0x2000, s23
	s_lshr_b32 s11, s30, s9
	s_and_b32 s10, s30, s10
	v_readlane_b32 s4, v12, s31
	s_add_u32 s31, s31, 1
	v_readlane_b32 s5, v12, s31
	s_mul_i32 s2, s2, s36
	s_lshl_b32 s9, s3, 2
	s_mul_i32 s8, s10, s9
	s_lshl_b32 s8, s8, 6
	s_add_u32 s2, s2, s8
	s_add_u32 s4, s4, s2
	s_addc_u32 s5, s5, 0
	s_mul_i32 s2, s11, s23
	s_lshl_b32 s2, s2, 6
	s_lshl_b32 s8, s10, 7
	s_add_u32 s2, s2, s8
	s_add_u32 s2, s2, s7
	s_mul_i32 s8, s36, 0x1a80000
	s_add_u32 s2, s2, s8
	s_add_u32 s44, s12, s2
	s_addc_u32 s45, s13, 0
	s_lshl_b32 s8, s11, 6
	s_sub_i32 s2, s3, s8
	v_cmp_gt_i32_e64 s[50:51], s2, v3
	s_lshl_b32 s8, s8, 2
	v_add_u32_e32 v13, s8, v2
	s_lshl_b32 s8, s9, 5
; #define LAS __attribute__((address_space(3)))
; __device__ __forceinline__ int tidx() { int t = threadIdx.x; asm volatile("" : "+v"(t)); return t; }
; __device__ __forceinline__ void tile_load(const TileJob& j, f32x4 (&v)[2]) {
;     const int tid = tidx(), k0 = j.tk * 64, n0 = j.tn * 64;
; #pragma unroll
;     for (int i = 0; i < 2; ++i) { const int r = (tid >> 4) + 32 * i, c = (tid & 15) * 4, n = n0 + c;
;         v[i] = (f32x4){0.f, 0.f, 0.f, 0.f};
;         if (n < j.Nreal) v[i] = *(const f32x4*)(j.W + (size_t)(k0 + r) * j.Nreal + n); }
; }
; __device__ __forceinline__ void tile_store(const TileJob& j, const f32x4 (&v)[2], LAS float* tile) {
;     const int tid = tidx(), k0 = j.tk * 64, n0 = j.tn * 64;
; #pragma unroll
;     for (int i = 0; i < 2; ++i) { const int r = (tid >> 4) + 32 * i, c = (tid & 15) * 4;
;         tile[r * 65 + c] = v[i][0]; tile[r * 65 + c + 1] = v[i][1]; tile[r * 65 + c + 2] = v[i][2]; tile[r * 65 + c + 3] = v[i][3]; }
;     __syncthreads();
;     { const int nl = tid >> 3, k8 = (tid & 7) * 8; u32x4 w;
;       w.x = pkh(tile[(k8 + 0) * 65 + nl], tile[(k8 + 1) * 65 + nl]); w.y = pkh(tile[(k8 + 2) * 65 + nl], tile[(k8 + 3) * 65 + nl]);
;       w.z = pkh(tile[(k8 + 4) * 65 + nl], tile[(k8 + 5) * 65 + nl]); w.w = pkh(tile[(k8 + 6) * 65 + nl], tile[(k8 + 7) * 65 + nl]);
;       *(u32x4*)(j.Bt + (size_t)(n0 + nl) * j.Kdim + k0 + k8) = w; }
;     __syncthreads();
; }
; __device__ __forceinline__ void convert_tiles(int t0, int t1, int step, LAS float* tile) {
;     int t = t0;
;     if (t < t1) {
;         TileJob cur = tile_job(t); f32x4 v[2]; tile_load(cur, v);
;         for (;;) {
;             const int tn = t + step; const bool more = tn < t1;
;             TileJob nxt = cur; f32x4 vn[2];
;             if (more) { nxt = tile_job(tn); tile_load(nxt, vn); }
;             tile_store(cur, v, tile);
;             if (!more) break;
;             cur = nxt; v[0] = vn[0]; v[1] = vn[1]; t = tn;
;         }
;     }
; }
	s_add_u32 s6, s4, s8
	s_addc_u32 s7, s5, 0
	v_cndmask_b32_e64 v13, 0, v13, s[50:51]
	v_mad_u32_u24 v13, v1, s9, v13
	global_load_dwordx4 v[28:31], v13, s[4:5]
	global_load_dwordx4 v[32:35], v13, s[6:7]
	s_add_u32 s26, s40, 2
	s_sub_u32 s9, s41, 1
	s_min_u32 s26, s26, s9
	s_cmp_ge_u32 s26, 0xd40
	s_cselect_b32 s36, 1, 0
	s_cselect_b32 s30, 0xd40, 0
	s_sub_u32 s30, s26, s30
	s_movk_i32 s31, 6
	s_mov_b32 s2, 0x1000000
	s_movk_i32 s3, 0x400
	s_movk_i32 s6, 0x940
	s_mov_b32 s7, 0x1280000
	s_cmp_lt_u32 s30, 0x940
	s_cselect_b32 s31, 4, s31
	s_cselect_b32 s3, 0x1000, s3
	s_cselect_b32 s6, 0x540, s6
	s_cselect_b32 s7, 0xa80000, s7
	s_cselect_b32 s8, 0, 1
	s_cmp_lt_u32 s30, 0x540
	s_cselect_b32 s31, 2, s31
	s_cselect_b32 s2, 0x400000, s2
	s_cselect_b32 s3, 0x400, s3
	s_cselect_b32 s6, 0x440, s6
	s_cselect_b32 s7, 0x880000, s7
	s_cmp_lt_u32 s30, 0x440
	s_cselect_b32 s31, 0, s31
	s_cselect_b32 s2, 0x100c000, s2
	s_cselect_b32 s3, 0x100c, s3
	s_cselect_b32 s6, 0, s6
	s_cselect_b32 s7, 0, s7
	s_sub_u32 s30, s30, s6
	s_cmp_eq_u32 s8, 1
	s_cselect_b32 s9, 6, 4
	s_cselect_b32 s10, 63, 15
	s_movk_i32 s25, 0x800
	s_cselect_b32 s25, 0x2000, s25
	s_lshr_b32 s11, s30, s9
	s_and_b32 s10, s30, s10
	v_readlane_b32 s4, v12, s31
	s_add_u32 s31, s31, 1
	v_readlane_b32 s5, v12, s31
	s_mul_i32 s2, s2, s36
	s_lshl_b32 s9, s3, 2
	s_mul_i32 s8, s10, s9
	s_lshl_b32 s8, s8, 6
	s_add_u32 s2, s2, s8
	s_add_u32 s4, s4, s2
	s_addc_u32 s5, s5, 0
	s_mul_i32 s2, s11, s25
	s_lshl_b32 s2, s2, 6
	s_lshl_b32 s8, s10, 7
	s_add_u32 s2, s2, s8
	s_add_u32 s2, s2, s7
	s_mul_i32 s8, s36, 0x1a80000
	s_add_u32 s2, s2, s8
	s_add_u32 s46, s12, s2
	s_addc_u32 s47, s13, 0
	s_lshl_b32 s8, s11, 6
	s_sub_i32 s2, s3, s8
	v_cmp_gt_i32_e64 s[100:101], s2, v3
	s_lshl_b32 s8, s8, 2
	v_add_u32_e32 v13, s8, v2
	s_lshl_b32 s8, s9, 5
	s_add_u32 s6, s4, s8
	s_addc_u32 s7, s5, 0
	v_cndmask_b32_e64 v13, 0, v13, s[100:101]
	v_mad_u32_u24 v13, v1, s9, v13
	global_load_dwordx4 v[36:39], v13, s[4:5]
	global_load_dwordx4 v[40:43], v13, s[6:7]
.Lcvt_loop:
	s_waitcnt vmcnt(4)
	v_cndmask_b32_e64 v20, 0, v20, s[48:49]
	v_cndmask_b32_e64 v21, 0, v21, s[48:49]
	v_cndmask_b32_e64 v22, 0, v22, s[48:49]
	v_cndmask_b32_e64 v23, 0, v23, s[48:49]
	v_cndmask_b32_e64 v24, 0, v24, s[48:49]
	v_cndmask_b32_e64 v25, 0, v25, s[48:49]
	v_cndmask_b32_e64 v26, 0, v26, s[48:49]
	v_cndmask_b32_e64 v27, 0, v27, s[48:49]
	ds_write2_b32 v6, v20, v21 offset1:1
	ds_write2_b32 v6, v22, v23 offset0:2 offset1:3
	ds_write2_b32 v10, v24, v25 offset1:1
	ds_write2_b32 v10, v26, v27 offset0:2 offset1:3
	s_waitcnt lgkmcnt(0)
	s_barrier
	ds_read2_b32 v[14:15], v7 offset1:65
	ds_read2_b32 v[18:19], v7 offset0:130 offset1:195
	ds_read2_b32 v[44:45], v11 offset1:65
	ds_read2_b32 v[46:47], v11 offset0:130 offset1:195
	v_mad_u32_u24 v48, v4, s22, v5
	s_waitcnt lgkmcnt(0)
	v_cvt_pk_f16_f32 v50, v14, v15
	v_cvt_pk_f16_f32 v51, v18, v19
	v_cvt_pk_f16_f32 v52, v44, v45
	v_cvt_pk_f16_f32 v53, v46, v47
	global_store_dwordx4 v48, v[50:53], s[42:43]
	s_add_u32 s26, s40, 3
	s_sub_u32 s9, s41, 1
	s_min_u32 s26, s26, s9
	s_cmp_ge_u32 s26, 0xd40
	s_cselect_b32 s36, 1, 0
	s_cselect_b32 s30, 0xd40, 0
	s_sub_u32 s30, s26, s30
	s_movk_i32 s31, 6
	s_mov_b32 s2, 0x1000000
	s_movk_i32 s3, 0x400
	s_movk_i32 s6, 0x940
	s_mov_b32 s7, 0x1280000
	s_cmp_lt_u32 s30, 0x940
	s_cselect_b32 s31, 4, s31
	s_cselect_b32 s3, 0x1000, s3
	s_cselect_b32 s6, 0x540, s6
	s_cselect_b32 s7, 0xa80000, s7
	s_cselect_b32 s8, 0, 1
	s_cmp_lt_u32 s30, 0x540
	s_cselect_b32 s31, 2, s31
	s_cselect_b32 s2, 0x400000, s2
	s_cselect_b32 s3, 0x400, s3
	s_cselect_b32 s6, 0x440, s6
	s_cselect_b32 s7, 0x880000, s7
	s_cmp_lt_u32 s30, 0x440
	s_cselect_b32 s31, 0, s31
	s_cselect_b32 s2, 0x100c000, s2
	s_cselect_b32 s3, 0x100c, s3
	s_cselect_b32 s6, 0, s6
	s_cselect_b32 s7, 0, s7
	s_sub_u32 s30, s30, s6
	s_cmp_eq_u32 s8, 1
	s_cselect_b32 s9, 6, 4
	s_cselect_b32 s10, 63, 15
	s_movk_i32 s22, 0x800
	s_cselect_b32 s22, 0x2000, s22
	s_lshr_b32 s11, s30, s9
	s_and_b32 s10, s30, s10
	v_readlane_b32 s4, v12, s31
	s_add_u32 s31, s31, 1
	v_readlane_b32 s5, v12, s31
	s_mul_i32 s2, s2, s36
	s_lshl_b32 s9, s3, 2
	s_mul_i32 s8, s10, s9
	s_lshl_b32 s8, s8, 6
	s_add_u32 s2, s2, s8
	s_add_u32 s4, s4, s2
	s_addc_u32 s5, s5, 0
	s_mul_i32 s2, s11, s22
	s_lshl_b32 s2, s2, 6
	s_lshl_b32 s8, s10, 7
	s_add_u32 s2, s2, s8
	s_add_u32 s2, s2, s7
	s_mul_i32 s8, s36, 0x1a80000
	s_add_u32 s2, s2, s8
	s_add_u32 s42, s12, s2
	s_addc_u32 s43, s13, 0
	s_lshl_b32 s8, s11, 6
	s_sub_i32 s2, s3, s8
	v_cmp_gt_i32_e64 s[48:49], s2, v3
	s_lshl_b32 s8, s8, 2
	v_add_u32_e32 v13, s8, v2
	s_lshl_b32 s8, s9, 5
	s_add_u32 s6, s4, s8
	s_addc_u32 s7, s5, 0
	v_cndmask_b32_e64 v13, 0, v13, s[48:49]
	v_mad_u32_u24 v13, v1, s9, v13
	global_load_dwordx4 v[20:23], v13, s[4:5]
	global_load_dwordx4 v[24:27], v13, s[6:7]
	s_barrier
	s_add_u32 s40, s40, 1
	s_cmp_ge_u32 s40, s41
	s_cbranch_scc1 .Lcvt_end
	s_waitcnt vmcnt(4)
	v_cndmask_b32_e64 v28, 0, v28, s[50:51]
	v_cndmask_b32_e64 v29, 0, v29, s[50:51]
	v_cndmask_b32_e64 v30, 0, v30, s[50:51]
	v_cndmask_b32_e64 v31, 0, v31, s[50:51]
	v_cndmask_b32_e64 v32, 0, v32, s[50:51]
	v_cndmask_b32_e64 v33, 0, v33, s[50:51]
	v_cndmask_b32_e64 v34, 0, v34, s[50:51]
	v_cndmask_b32_e64 v35, 0, v35, s[50:51]
	ds_write2_b32 v6, v28, v29 offset1:1
	ds_write2_b32 v6, v30, v31 offset0:2 offset1:3
	ds_write2_b32 v10, v32, v33 offset1:1
	ds_write2_b32 v10, v34, v35 offset0:2 offset1:3
	s_waitcnt lgkmcnt(0)
	s_barrier
; #define LAS __attribute__((address_space(3)))
; __device__ __forceinline__ int tidx() { int t = threadIdx.x; asm volatile("" : "+v"(t)); return t; }
; __device__ __forceinline__ void tile_store(const TileJob& j, const f32x4 (&v)[2], LAS float* tile) {
;     const int tid = tidx(), k0 = j.tk * 64, n0 = j.tn * 64;
; #pragma unroll
;     for (int i = 0; i < 2; ++i) { const int r = (tid >> 4) + 32 * i, c = (tid & 15) * 4;
;         tile[r * 65 + c] = v[i][0]; tile[r * 65 + c + 1] = v[i][1]; tile[r * 65 + c + 2] = v[i][2]; tile[r * 65 + c + 3] = v[i][3]; }
;     __syncthreads();
;     { const int nl = tid >> 3, k8 = (tid & 7) * 8; u32x4 w;
;       w.x = pkh(tile[(k8 + 0) * 65 + nl], tile[(k8 + 1) * 65 + nl]); w.y = pkh(tile[(k8 + 2) * 65 + nl], tile[(k8 + 3) * 65 + nl]);
;       w.z = pkh(tile[(k8 + 4) * 65 + nl], tile[(k8 + 5) * 65 + nl]); w.w = pkh(tile[(k8 + 6) * 65 + nl], tile[(k8 + 7) * 65 + nl]);
;       *(u32x4*)(j.Bt + (size_t)(n0 + nl) * j.Kdim + k0 + k8) = w; }
;     __syncthreads();
; }
; __device__ __forceinline__ void convert_tiles(int t0, int t1, int step, LAS float* tile) {
;     int t = t0;
;     if (t < t1) {
;         TileJob cur = tile_job(t); f32x4 v[2]; tile_load(cur, v);
;         for (;;) {
;             const int tn = t + step; const bool more = tn < t1;
;             TileJob nxt = cur; f32x4 vn[2];
;             if (more) { nxt = tile_job(tn); tile_load(nxt, vn); }
;             tile_store(cur, v, tile);
;             if (!more) break;
;             cur = nxt; v[0] = vn[0]; v[1] = vn[1]; t = tn;
;         }
;     }
; }
	ds_read2_b32 v[14:15], v7 offset1:65
	ds_read2_b32 v[18:19], v7 offset0:130 offset1:195
	ds_read2_b32 v[44:45], v11 offset1:65
	ds_read2_b32 v[46:47], v11 offset0:130 offset1:195
	v_mad_u32_u24 v48, v4, s23, v5
	s_waitcnt lgkmcnt(0)
	v_cvt_pk_f16_f32 v50, v14, v15
	v_cvt_pk_f16_f32 v51, v18, v19
	v_cvt_pk_f16_f32 v52, v44, v45
	v_cvt_pk_f16_f32 v53, v46, v47
	global_store_dwordx4 v48, v[50:53], s[44:45]
	s_add_u32 s26, s40, 3
	s_sub_u32 s9, s41, 1
	s_min_u32 s26, s26, s9
	s_cmp_ge_u32 s26, 0xd40
	s_cselect_b32 s36, 1, 0
	s_cselect_b32 s30, 0xd40, 0
	s_sub_u32 s30, s26, s30
	s_movk_i32 s31, 6
	s_mov_b32 s2, 0x1000000
	s_movk_i32 s3, 0x400
	s_movk_i32 s6, 0x940
	s_mov_b32 s7, 0x1280000
	s_cmp_lt_u32 s30, 0x940
	s_cselect_b32 s31, 4, s31
	s_cselect_b32 s3, 0x1000, s3
	s_cselect_b32 s6, 0x540, s6
	s_cselect_b32 s7, 0xa80000, s7
	s_cselect_b32 s8, 0, 1
	s_cmp_lt_u32 s30, 0x540
	s_cselect_b32 s31, 2, s31
	s_cselect_b32 s2, 0x400000, s2
	s_cselect_b32 s3, 0x400, s3
	s_cselect_b32 s6, 0x440, s6
	s_cselect_b32 s7, 0x880000, s7
	s_cmp_lt_u32 s30, 0x440
	s_cselect_b32 s31, 0, s31
	s_cselect_b32 s2, 0x100c000, s2
	s_cselect_b32 s3, 0x100c, s3
	s_cselect_b32 s6, 0, s6
	s_cselect_b32 s7, 0, s7
	s_sub_u32 s30, s30, s6
	s_cmp_eq_u32 s8, 1
	s_cselect_b32 s9, 6, 4
	s_cselect_b32 s10, 63, 15
	s_movk_i32 s23, 0x800
	s_cselect_b32 s23, 0x2000, s23
	s_lshr_b32 s11, s30, s9
	s_and_b32 s10, s30, s10
	v_readlane_b32 s4, v12, s31
	s_add_u32 s31, s31, 1
	v_readlane_b32 s5, v12, s31
	s_mul_i32 s2, s2, s36
	s_lshl_b32 s9, s3, 2
	s_mul_i32 s8, s10, s9
	s_lshl_b32 s8, s8, 6
	s_add_u32 s2, s2, s8
	s_add_u32 s4, s4, s2
	s_addc_u32 s5, s5, 0
	s_mul_i32 s2, s11, s23
	s_lshl_b32 s2, s2, 6
	s_lshl_b32 s8, s10, 7
	s_add_u32 s2, s2, s8
	s_add_u32 s2, s2, s7
	s_mul_i32 s8, s36, 0x1a80000
	s_add_u32 s2, s2, s8
	s_add_u32 s44, s12, s2
	s_addc_u32 s45, s13, 0
	s_lshl_b32 s8, s11, 6
	s_sub_i32 s2, s3, s8
	v_cmp_gt_i32_e64 s[50:51], s2, v3
	s_lshl_b32 s8, s8, 2
	v_add_u32_e32 v13, s8, v2
	s_lshl_b32 s8, s9, 5
	s_add_u32 s6, s4, s8
	s_addc_u32 s7, s5, 0
	v_cndmask_b32_e64 v13, 0, v13, s[50:51]
	v_mad_u32_u24 v13, v1, s9, v13
	global_load_dwordx4 v[28:31], v13, s[4:5]
	global_load_dwordx4 v[32:35], v13, s[6:7]
	s_barrier
	s_add_u32 s40, s40, 1
	s_cmp_ge_u32 s40, s41
	s_cbranch_scc1 .Lcvt_end
	s_waitcnt vmcnt(4)
	v_cndmask_b32_e64 v36, 0, v36, s[100:101]
	v_cndmask_b32_e64 v37, 0, v37, s[100:101]
	v_cndmask_b32_e64 v38, 0, v38, s[100:101]
	v_cndmask_b32_e64 v39, 0, v39, s[100:101]
	v_cndmask_b32_e64 v40, 0, v40, s[100:101]
	v_cndmask_b32_e64 v41, 0, v41, s[100:101]
	v_cndmask_b32_e64 v42, 0, v42, s[100:101]
	v_cndmask_b32_e64 v43, 0, v43, s[100:101]
	ds_write2_b32 v6, v36, v37 offset1:1
	ds_write2_b32 v6, v38, v39 offset0:2 offset1:3
	ds_write2_b32 v10, v40, v41 offset1:1
	ds_write2_b32 v10, v42, v43 offset0:2 offset1:3
	s_waitcnt lgkmcnt(0)
	s_barrier
	ds_read2_b32 v[14:15], v7 offset1:65
	ds_read2_b32 v[18:19], v7 offset0:130 offset1:195
	ds_read2_b32 v[44:45], v11 offset1:65
	ds_read2_b32 v[46:47], v11 offset0:130 offset1:195
	v_mad_u32_u24 v48, v4, s25, v5
	s_waitcnt lgkmcnt(0)
	v_cvt_pk_f16_f32 v50, v14, v15
	v_cvt_pk_f16_f32 v51, v18, v19
	v_cvt_pk_f16_f32 v52, v44, v45
	v_cvt_pk_f16_f32 v53, v46, v47
	global_store_dwordx4 v48, v[50:53], s[46:47]
	s_add_u32 s26, s40, 3
	s_sub_u32 s9, s41, 1
	s_min_u32 s26, s26, s9
	s_cmp_ge_u32 s26, 0xd40
	s_cselect_b32 s36, 1, 0
	s_cselect_b32 s30, 0xd40, 0
	s_sub_u32 s30, s26, s30
	s_movk_i32 s31, 6
	s_mov_b32 s2, 0x1000000
	s_movk_i32 s3, 0x400
	s_movk_i32 s6, 0x940
	s_mov_b32 s7, 0x1280000
	s_cmp_lt_u32 s30, 0x940
	s_cselect_b32 s31, 4, s31
	s_cselect_b32 s3, 0x1000, s3
	s_cselect_b32 s6, 0x540, s6
	s_cselect_b32 s7, 0xa80000, s7
	s_cselect_b32 s8, 0, 1
	s_cmp_lt_u32 s30, 0x540
	s_cselect_b32 s31, 2, s31
	s_cselect_b32 s2, 0x400000, s2
	s_cselect_b32 s3, 0x400, s3
	s_cselect_b32 s6, 0x440, s6
	s_cselect_b32 s7, 0x880000, s7
	s_cmp_lt_u32 s30, 0x440
	s_cselect_b32 s31, 0, s31
	s_cselect_b32 s2, 0x100c000, s2
	s_cselect_b32 s3, 0x100c, s3
	s_cselect_b32 s6, 0, s6
	s_cselect_b32 s7, 0, s7
	s_sub_u32 s30, s30, s6
	s_cmp_eq_u32 s8, 1
	s_cselect_b32 s9, 6, 4
	s_cselect_b32 s10, 63, 15
	s_movk_i32 s25, 0x800
	s_cselect_b32 s25, 0x2000, s25
	s_lshr_b32 s11, s30, s9
	s_and_b32 s10, s30, s10
	v_readlane_b32 s4, v12, s31
	s_add_u32 s31, s31, 1
	v_readlane_b32 s5, v12, s31
	s_mul_i32 s2, s2, s36
	s_lshl_b32 s9, s3, 2
	s_mul_i32 s8, s10, s9
	s_lshl_b32 s8, s8, 6
	s_add_u32 s2, s2, s8
	s_add_u32 s4, s4, s2
	s_addc_u32 s5, s5, 0
	s_mul_i32 s2, s11, s25
	s_lshl_b32 s2, s2, 6
	s_lshl_b32 s8, s10, 7
	s_add_u32 s2, s2, s8
	s_add_u32 s2, s2, s7
	s_mul_i32 s8, s36, 0x1a80000
	s_add_u32 s2, s2, s8
	s_add_u32 s46, s12, s2
	s_addc_u32 s47, s13, 0
	s_lshl_b32 s8, s11, 6
	s_sub_i32 s2, s3, s8
	v_cmp_gt_i32_e64 s[100:101], s2, v3
	s_lshl_b32 s8, s8, 2
	v_add_u32_e32 v13, s8, v2
	s_lshl_b32 s8, s9, 5
	s_add_u32 s6, s4, s8
	s_addc_u32 s7, s5, 0
	v_cndmask_b32_e64 v13, 0, v13, s[100:101]
	v_mad_u32_u24 v13, v1, s9, v13
	global_load_dwordx4 v[36:39], v13, s[4:5]
	global_load_dwordx4 v[40:43], v13, s[6:7]
	s_barrier
	s_add_u32 s40, s40, 1
	s_cmp_ge_u32 s40, s41
	s_cbranch_scc1 .Lcvt_end
	s_branch .Lcvt_loop
.Lcvt_end:
	s_waitcnt vmcnt(0)
.Lcvt_none:
	s_mov_b64 s[4:5], 0
.LBB0_997:
	s_and_b64 vcc, exec, s[4:5]
	s_cbranch_vccz .LBB0_1059
	s_mov_b32 s2, s17
	s_cmpk_gt_i32 s2, 0x43f
	s_cbranch_scc1 .LBB0_1011
	s_mov_b64 s[6:7], s[0:1]
	s_mov_b64 s[4:5], s[0:1]
	s_ashr_i32 s3, s2, 31
	s_lshr_b32 s3, s3, 28
	s_load_dwordx2 s[4:5], s[4:5], 0x48
	s_add_i32 s8, s2, s3
	s_ashr_i32 s3, s8, 4
	s_and_b32 s8, s8, -16
	s_waitcnt vmcnt(0)
	v_mov_b32_e32 v0, v202
	s_sub_i32 s12, s2, s8
	s_lshl_b32 s8, s3, 6
	v_lshlrev_b32_e32 v1, 2, v0
	v_and_or_b32 v8, v1, 60, s8
	v_ashrrev_i32_e32 v0, 4, v0
	s_movk_i32 s8, 0x100c
	v_lshl_add_u32 v10, s12, 6, v0
	v_ashrrev_i32_e32 v9, 31, v8
	v_cmp_gt_i32_e32 vcc, s8, v8
	v_mov_b32_e32 v4, 0
	v_mov_b32_e32 v0, 0
	v_mov_b32_e32 v1, 0
	v_mov_b32_e32 v2, 0
	v_mov_b32_e32 v3, 0
	s_and_saveexec_b64 s[8:9], vcc
	s_cbranch_execz .LBB0_1001
	s_waitcnt lgkmcnt(0)
	v_mov_b64_e32 v[0:1], s[4:5]
	s_movk_i32 s10, 0x4030
	v_mad_i64_i32 v[0:1], s[10:11], v10, s10, v[0:1]
	v_lshl_add_u64 v[0:1], v[8:9], 2, v[0:1]
	global_load_dwordx4 v[0:3], v[0:1], off

; __global__ void __launch_bounds__(512, 2) hymba_fwd(Params p) {
;     extern __shared__ __attribute__((aligned(16))) unsigned char shm[];
	.amdhsa_kernel _Z9hymba_fwd6Params
		.amdhsa_group_segment_fixed_size 0
		.amdhsa_private_segment_fixed_size 0
		.amdhsa_kernarg_size 488
		.amdhsa_user_sgpr_count 2
		.amdhsa_user_sgpr_dispatch_ptr 0
		.amdhsa_user_sgpr_queue_ptr 0
		.amdhsa_user_sgpr_kernarg_segment_ptr 1
		.amdhsa_user_sgpr_dispatch_id 0
		.amdhsa_user_sgpr_kernarg_preload_length 0
		.amdhsa_user_sgpr_kernarg_preload_offset 0
		.amdhsa_user_sgpr_private_segment_size 0
		.amdhsa_uses_dynamic_stack 0
		.amdhsa_enable_private_segment 0
		.amdhsa_system_sgpr_workgroup_id_x 1
		.amdhsa_system_sgpr_workgroup_id_y 0
		.amdhsa_system_sgpr_workgroup_id_z 0
		.amdhsa_system_sgpr_workgroup_info 0
		.amdhsa_system_vgpr_workitem_id 2
		.amdhsa_next_free_vgpr 254
		.amdhsa_next_free_sgpr 102
		.amdhsa_accum_offset 256
		.amdhsa_reserve_vcc 1
		.amdhsa_float_round_mode_32 0
		.amdhsa_float_round_mode_16_64 0
		.amdhsa_float_denorm_mode_32 3
		.amdhsa_float_denorm_mode_16_64 3
		.amdhsa_dx10_clamp 1
		.amdhsa_ieee_mode 1
		.amdhsa_fp16_overflow 0
		.amdhsa_tg_split 0
		.amdhsa_exception_fp_ieee_invalid_op 0
		.amdhsa_exception_fp_denorm_src 0
		.amdhsa_exception_fp_ieee_div_zero 0
		.amdhsa_exception_fp_ieee_overflow 0
		.amdhsa_exception_fp_ieee_underflow 0
		.amdhsa_exception_fp_ieee_inexact 0
		.amdhsa_exception_int_div_zero 0
	.end_amdhsa_kernel

; __global__ void __launch_bounds__(512, 2) hymba_fwd(Params p) {
;     extern __shared__ __attribute__((aligned(16))) unsigned char shm[];
amdhsa.kernels:
  - .agpr_count:     0
    .args:
      - .offset:         0
        .size:           232
        .value_kind:     by_value
      - .offset:         232
        .size:           4
        .value_kind:     hidden_block_count_x
      - .offset:         236
        .size:           4
        .value_kind:     hidden_block_count_y
      - .offset:         240
        .size:           4
        .value_kind:     hidden_block_count_z
      - .offset:         244
        .size:           2
        .value_kind:     hidden_group_size_x
      - .offset:         246
        .size:           2
        .value_kind:     hidden_group_size_y
      - .offset:         248
        .size:           2
        .value_kind:     hidden_group_size_z
      - .offset:         250
        .size:           2
        .value_kind:     hidden_remainder_x
      - .offset:         252
        .size:           2
        .value_kind:     hidden_remainder_y
      - .offset:         254
        .size:           2
        .value_kind:     hidden_remainder_z
      - .offset:         272
        .size:           8
        .value_kind:     hidden_global_offset_x
      - .offset:         280
        .size:           8
        .value_kind:     hidden_global_offset_y
      - .offset:         288
        .size:           8
        .value_kind:     hidden_global_offset_z
      - .offset:         296
        .size:           2
        .value_kind:     hidden_grid_dims
      - .offset:         320
        .size:           8
        .value_kind:     hidden_multigrid_sync_arg
      - .offset:         352
        .size:           4
        .value_kind:     hidden_dynamic_lds_size
    .group_segment_fixed_size: 0
    .kernarg_segment_align: 8
    .kernarg_segment_size: 488
    .language:       OpenCL C
    .language_version:
      - 2
      - 0
    .max_flat_workgroup_size: 512
    .name:           _Z9hymba_fwd6Params
    .private_segment_fixed_size: 0
    .sgpr_count:     108
    .sgpr_spill_count: 152
    .symbol:         _Z9hymba_fwd6Params.kd
    .uniform_work_group_size: 1
    .uses_dynamic_stack: false
    .vgpr_count:     254
    .vgpr_spill_count: 0
    .wavefront_size: 64
